# C2 static load balance (second item index xor 128: one heavy + one light rwkv_fin item per workgroup) + XCD-aware order in phase A
# speedup vs baseline: 1.1727x; 1.0119x over previous
; __device__ __forceinline__ float bf2f(unsigned short b) { return __uint_as_float(((unsigned)b) << 16); }
; __device__ __forceinline__ float sigmoidf_(float x) { return __builtin_amdgcn_rcpf(1.0f + __expf(-x)); }
; __device__ __forceinline__ void rwkv_fin_item(const Params& p, int l, int item, char* ldsraw) {
;     ...
;   const int tok0 = item * 16, b = tok0 >> 12, s0 = tok0 & 4095;
;   const float* mu = p.mu + l * 896;
; #pragma unroll
;   for (int i = 0; i < 4; i++) {
;     int idx = tid + 256 * i; int t = idx >> 6, c = idx & 63;
;     int col = C_RW + 832 + c; int tok = tok0 + t;
;     float cur = bf2f(P[(size_t)tok * PIN + col]);
;     float prv = (s0 + t > 0) ? bf2f(P[(size_t)(tok - 1) * PIN + col]) : 0.f;
;     float v = cur + (prv - cur) * mu[832 + c];
;     lds[t * 64 + c] = sigmoidf_(v);
;   }
.LBB0_140:
	s_mov_b32 s2, s89
	s_add_u32 s28, s46, s2
	s_mov_b32 s3, s89
	s_mov_b32 s2, s89
	s_mov_b32 s27, s89
	s_waitcnt vmcnt(4)
	v_mov_b32_e32 v0, v198
	s_addc_u32 s29, s47, 0
	v_and_b32_e32 v57, 63, v0
	v_lshlrev_b32_e32 v2, 1, v57
	s_lshr_b32 s26, s31, 9
	s_lshl_b32 s26, s26, 7
	s_xor_b32 s26, s26, s31
	s_lshl_b32 s26, s26, 4
	v_lshl_add_u64 v[4:5], s[28:29], 0, v[2:3]
	s_mov_b64 s[28:29], 0x768b00
	v_ashrrev_i32_e32 v16, 6, v0
	v_lshl_add_u64 v[4:5], v[4:5], 0, s[28:29]
	v_add_u32_e32 v7, s26, v16
	v_mad_i64_i32 v[8:9], s[28:29], v7, s69, v[4:5]
	global_load_ushort v1, v[8:9], off
	s_and_b32 s36, s26, 0xff0
	s_sub_i32 s37, 0, s36
	v_cmp_lt_i32_e32 vcc, s37, v16
	v_mov_b32_e32 v6, 0
	v_mov_b32_e32 v8, 0
	s_and_saveexec_b64 s[28:29], vcc
	s_cbranch_execz .LBB0_142
	v_add_u32_e32 v7, -1, v7
	v_mad_i64_i32 v[8:9], s[38:39], v7, s69, v[4:5]
	global_load_ushort v7, v[8:9], off
	s_waitcnt vmcnt(0)
	v_lshlrev_b32_e32 v8, 16, v7

; __device__ __forceinline__ unsigned char* WS(const Params& p) { unsigned z = 0; asm volatile("" : "+s"(z)); return p.ws + z; }
; __device__ __forceinline__ void gemm_mainloop_d(const bf16_t* __restrict__ Ap, int lda, const bf16_t* __restrict__ Bt, int K,
;                                                 int m0, int n0, f32x4 (&acc)[4][4], char* lds) {
;     ...
; #pragma unroll
;   for (int m = 0; m < 4; m++)
; #pragma unroll
;     for (int n = 0; n < 4; n++) acc[m][n] = (f32x4){0.f, 0.f, 0.f, 0.f};
;   const int nk = K >> 6;
;   const int lrow = tid >> 3, cph = tid & 7;
;   auto dma = [&](int kt, int st) {
;     char* la = lds + st * 32768; char* lb = la + 16384;
; #pragma unroll
;     for (int i = 0; i < 4; i++) {
;       const int row = i * 32 + lrow; const int c = cph ^ ((row >> 1) & 7);
;       __builtin_amdgcn_global_load_lds((const unsigned*)(Ap + (size_t)(m0 + row) * lda + kt * 64 + c * 8), (__attribute__((address_space(3))) unsigned*)(la + i * 4096 + tid * 16), 16, 0, 0);
;       __builtin_amdgcn_global_load_lds((const unsigned*)(Bt + (size_t)(n0 + row) * K + kt * 64 + c * 8), (__attribute__((address_space(3))) unsigned*)(lb + i * 4096 + tid * 16), 16, 0, 0);
;     }
;   };
;   dma(0, 0);
;   asm volatile("s_waitcnt vmcnt(0)" ::: "memory"); __builtin_amdgcn_s_barrier(); asm volatile("" ::: "memory");
; __device__ __forceinline__ void gemm_A(const Params& p, int item, char* lds) {
;   const int mt = item / 18, nt = item % 18; const int m0 = mt * 128, n0 = nt * 128;
;   f32x4 acc[4][4];
;   gemm_mainloop_d((const bf16_t*)(WS(p) + OFF_XB), DM, (const bf16_t*)(WS(p) + OFF_WIN), DM, m0, n0, acc, lds);
.LBB0_656:
	s_lshr_b32 s3, s66, 3
	s_mul_hi_u32 s30, s3, 0xe38e38f
	s_mul_i32 s31, s30, 18
	s_sub_u32 s2, s3, s31
	s_and_b32 s31, s66, 7
	s_lshl_b32 s30, s30, 3
	s_add_u32 s30, s30, s31
	s_lshl_b32 s24, s30, 7
	s_lshl_b32 s3, s2, 7
	s_mov_b32 s30, 0
	s_mov_b32 s31, 0
	v_mov_b32_e32 v20, v198
	s_add_u32 s26, s46, s30
	s_addc_u32 s27, s47, 0
	v_ashrrev_i32_e32 v16, 3, v20
	v_lshrrev_b32_e32 v23, 1, v16
	v_add_u32_e32 v0, s24, v16
	s_add_u32 s28, s26, 0x65a8000
	v_xor_b32_e32 v2, v23, v20
	v_ashrrev_i32_e32 v1, 31, v0
	s_addc_u32 s29, s27, 0
	v_lshlrev_b64 v[0:1], 11, v[0:1]
	v_lshlrev_b32_e32 v2, 4, v2
	v_lshl_add_u32 v82, v20, 4, 0
	s_waitcnt lgkmcnt(0)
	v_lshl_add_u64 v[4:5], s[28:29], 0, v[0:1]
	v_and_b32_e32 v2, 0x70, v2
	v_readfirstlane_b32 s34, v82
	s_add_u32 s26, s46, s31
	v_lshl_add_u64 v[4:5], v[4:5], 0, v[2:3]
	s_mov_b32 m0, s34
	s_addc_u32 s27, s47, 0
	global_load_lds_dwordx4 v[4:5], off
	v_add_u32_e32 v4, s3, v16
	s_add_u32 s26, s26, 0x8000
	v_ashrrev_i32_e32 v5, 31, v4
	s_addc_u32 s27, s27, 0
	v_lshlrev_b64 v[4:5], 11, v[4:5]
	v_add_u32_e32 v8, 0x4000, v82
	v_lshl_add_u64 v[6:7], s[26:27], 0, v[4:5]
	v_readfirstlane_b32 s34, v8
	v_lshl_add_u64 v[6:7], v[6:7], 0, v[2:3]
	s_mov_b32 m0, s34
	v_add_u32_e32 v10, 32, v16
	global_load_lds_dwordx4 v[6:7], off
	v_add_u32_e32 v6, s24, v10
	v_ashrrev_i32_e32 v7, 31, v6
	v_lshlrev_b64 v[6:7], 11, v[6:7]
	v_add_u32_e32 v11, 0x1000, v82
	v_lshl_add_u64 v[8:9], s[28:29], 0, v[6:7]
	v_readfirstlane_b32 s34, v11
	v_lshl_add_u64 v[8:9], v[8:9], 0, v[2:3]
	s_mov_b32 m0, s34
	v_add_u32_e32 v12, 0x5000, v82
	global_load_lds_dwordx4 v[8:9], off
	v_add_u32_e32 v8, s3, v10
	v_ashrrev_i32_e32 v9, 31, v8
	v_lshlrev_b64 v[8:9], 11, v[8:9]
	v_lshl_add_u64 v[10:11], s[26:27], 0, v[8:9]
	v_readfirstlane_b32 s34, v12
	v_lshl_add_u64 v[10:11], v[10:11], 0, v[2:3]
	s_mov_b32 m0, s34
	v_add_u32_e32 v14, 64, v16
	global_load_lds_dwordx4 v[10:11], off
	v_add_u32_e32 v10, s24, v14
	v_ashrrev_i32_e32 v11, 31, v10
	v_lshlrev_b64 v[10:11], 11, v[10:11]
	v_add_u32_e32 v15, 0x2000, v82
	v_lshl_add_u64 v[12:13], s[28:29], 0, v[10:11]
	v_readfirstlane_b32 s34, v15
	v_lshl_add_u64 v[12:13], v[12:13], 0, v[2:3]
	s_mov_b32 m0, s34
	v_add_u32_e32 v17, 0x6000, v82
	global_load_lds_dwordx4 v[12:13], off
	v_add_u32_e32 v12, s3, v14
	v_ashrrev_i32_e32 v13, 31, v12
	v_lshlrev_b64 v[12:13], 11, v[12:13]
	v_lshl_add_u64 v[14:15], s[26:27], 0, v[12:13]
	v_readfirstlane_b32 s34, v17
	v_lshl_add_u64 v[14:15], v[14:15], 0, v[2:3]
	s_mov_b32 m0, s34
	v_add_u32_e32 v18, 0x60, v16
	global_load_lds_dwordx4 v[14:15], off
	v_add_u32_e32 v14, s24, v18
	v_ashrrev_i32_e32 v15, 31, v14
	v_lshlrev_b64 v[14:15], 11, v[14:15]
	v_add_u32_e32 v19, 0x3000, v82
	v_lshl_add_u64 v[16:17], s[28:29], 0, v[14:15]
	v_readfirstlane_b32 s28, v19
	v_lshl_add_u64 v[16:17], v[16:17], 0, v[2:3]
	s_mov_b32 m0, s28
	s_mov_b32 s4, 0x1ffffc0
	global_load_lds_dwordx4 v[16:17], off
	v_add_u32_e32 v16, s3, v18
	v_ashrrev_i32_e32 v17, 31, v16
	v_lshlrev_b64 v[16:17], 11, v[16:17]
	v_lshl_add_u64 v[18:19], s[26:27], 0, v[16:17]
	v_lshl_add_u64 v[18:19], v[18:19], 0, v[2:3]
	v_add_u32_e32 v2, 0x7000, v82
	v_lshrrev_b32_e32 v21, 4, v20
	v_readfirstlane_b32 s26, v2
	s_mov_b32 m0, s26
	v_and_b32_e32 v2, 15, v20
	global_load_lds_dwordx4 v[18:19], off
	v_lshrrev_b32_e32 v18, 1, v20
	v_bfe_u32 v22, v20, 4, 2
	v_and_or_b32 v2, v18, s4, v2
	v_bfe_u32 v18, v20, 1, 3
	v_lshlrev_b32_e32 v19, 7, v20
	v_bitop3_b32 v21, v21, v18, 3 bitop3:0x6c
	v_bitop3_b32 v18, v22, v18, 4 bitop3:0x36
	v_readlane_b32 s4, v254, 44
	v_and_b32_e32 v19, 0x2780, v19
	v_lshlrev_b32_e32 v21, 4, v21
	v_lshlrev_b32_e32 v2, 7, v2
	v_lshlrev_b32_e32 v18, 4, v18
	s_add_u32 s26, s4, s30
	v_readlane_b32 s4, v254, 45
	v_or_b32_e32 v85, v2, v21
	v_or_b32_e32 v83, v18, v2
	v_or_b32_e32 v2, v18, v19
	v_bitop3_b32 v18, v23, 7, v20 bitop3:0x48
	s_addc_u32 s27, s4, 0
	v_readlane_b32 s4, v254, 62
	v_lshlrev_b32_e32 v18, 4, v18
	s_add_u32 s28, s4, s31
	v_readlane_b32 s4, v254, 63
	s_waitcnt vmcnt(0)
	s_barrier
	v_or_b32_e32 v4, v4, v18
	s_addc_u32 s29, s4, 0
	v_or_b32_e32 v0, v0, v18
	s_waitcnt vmcnt(0)
	v_lshl_add_u64 v[68:69], s[28:29], 0, v[4:5]
	v_or_b32_e32 v6, v6, v18
	v_or_b32_e32 v8, v8, v18
	v_or_b32_e32 v10, v10, v18
	v_or_b32_e32 v12, v12, v18
	v_or_b32_e32 v14, v14, v18
	v_or_b32_e32 v16, v16, v18
	v_mov_b32_e32 v4, 0
	s_mov_b32 s25, 0
	v_or_b32_e32 v84, v21, v19
	v_lshl_add_u64 v[0:1], s[26:27], 0, v[0:1]
	v_lshl_add_u64 v[70:71], s[26:27], 0, v[6:7]
	v_lshl_add_u64 v[72:73], s[28:29], 0, v[8:9]
	v_lshl_add_u64 v[74:75], s[26:27], 0, v[10:11]
	v_lshl_add_u64 v[76:77], s[28:29], 0, v[12:13]
	v_lshl_add_u64 v[78:79], s[26:27], 0, v[14:15]
	v_lshl_add_u64 v[80:81], s[28:29], 0, v[16:17]
	s_mov_b64 s[26:27], 0
	v_mov_b32_e32 v5, v4
	v_mov_b32_e32 v6, v4
	v_mov_b32_e32 v7, v4
	v_mov_b32_e32 v8, v4
	v_mov_b32_e32 v9, v4
	v_mov_b32_e32 v10, v4
	v_mov_b32_e32 v11, v4
	v_mov_b32_e32 v12, v4
	v_mov_b32_e32 v13, v4
	v_mov_b32_e32 v14, v4
	v_mov_b32_e32 v15, v4
	v_mov_b32_e32 v16, v4
	v_mov_b32_e32 v17, v4
	v_mov_b32_e32 v18, v4
	v_mov_b32_e32 v19, v4
	v_mov_b32_e32 v20, v4
	v_mov_b32_e32 v21, v4
	v_mov_b32_e32 v22, v4
	v_mov_b32_e32 v23, v4
	v_mov_b32_e32 v24, v4
	v_mov_b32_e32 v25, v4
	v_mov_b32_e32 v26, v4
	v_mov_b32_e32 v27, v4
	v_mov_b32_e32 v28, v4
	v_mov_b32_e32 v29, v4
	v_mov_b32_e32 v30, v4
	v_mov_b32_e32 v31, v4
	v_mov_b32_e32 v32, v4
	v_mov_b32_e32 v33, v4
	v_mov_b32_e32 v34, v4
	v_mov_b32_e32 v35, v4
	v_mov_b32_e32 v36, v4
	v_mov_b32_e32 v37, v4
	v_mov_b32_e32 v38, v4
	v_mov_b32_e32 v39, v4
	v_mov_b32_e32 v40, v4
	v_mov_b32_e32 v41, v4
	v_mov_b32_e32 v42, v4
	v_mov_b32_e32 v43, v4
	v_mov_b32_e32 v44, v4
	v_mov_b32_e32 v45, v4
	v_mov_b32_e32 v46, v4
	v_mov_b32_e32 v47, v4
	v_mov_b32_e32 v48, v4
	v_mov_b32_e32 v49, v4
	v_mov_b32_e32 v50, v4
	v_mov_b32_e32 v51, v4
	v_mov_b32_e32 v52, v4
	v_mov_b32_e32 v53, v4
	v_mov_b32_e32 v54, v4
	v_mov_b32_e32 v55, v4
	v_mov_b32_e32 v56, v4
	v_mov_b32_e32 v57, v4
	v_mov_b32_e32 v58, v4
	v_mov_b32_e32 v59, v4
	v_mov_b32_e32 v60, v4
	v_mov_b32_e32 v61, v4
	v_mov_b32_e32 v62, v4
	v_mov_b32_e32 v63, v4
	v_mov_b32_e32 v64, v4
	v_mov_b32_e32 v65, v4
	v_mov_b32_e32 v66, v4
	v_mov_b32_e32 v67, v4
